# P7, P8, P10 K-loops also use the SGPR-base + VGPR-offset LDS-DMA form (64-bit VALU address adds removed)
# speedup vs baseline: 1.0055x; 1.0055x over previous
.LBB0_640:
	ds_read_b128 v[144:147], v153
	ds_read_b128 v[156:159], v153 offset:1024
	ds_read_b128 v[160:163], v153 offset:2048
	ds_read_b128 v[164:167], v153 offset:3072
	ds_read_b128 v[168:171], v154
	ds_read_b128 v[172:175], v154 offset:1024
	ds_read_b128 v[176:179], v154 offset:2048
	ds_read_b128 v[180:183], v154 offset:3072
	s_add_u32 s28, s12, 0xfffc0080
	s_addc_u32 s29, s13, -1
	s_cmp_eq_u32 s27, 12
	s_cselect_b32 s57, s11, s29
	s_cselect_b32 s56, s14, s28
	s_cselect_b32 s55, s15, s26
	s_cselect_b32 s54, s24, s25
	s_add_i32 m0, s19, 0xc000
	ds_read_b128 v[184:187], v155
	ds_read_b128 v[188:191], v155 offset:1024
	ds_read_b128 v[192:195], v155 offset:2048
	ds_read_b128 v[196:199], v155 offset:3072
	ds_read_b128 v[200:203], v155 offset:4096
	ds_read_b128 v[204:207], v155 offset:5120
	ds_read_b128 v[208:211], v155 offset:6144
	ds_read_b128 v[216:219], v155 offset:7168
	global_load_lds_dwordx4 v136, s[12:13]
	s_add_i32 m0, s19, 0xe000
	s_nop 0
	global_load_lds_dwordx4 v138, s[12:13]
	s_waitcnt vmcnt(8)
	s_waitcnt lgkmcnt(0)
	s_barrier
	s_setprio 1
	s_waitcnt lgkmcnt(0)
	v_mfma_f32_16x16x32_bf16 v[124:127], v[144:147], v[184:187], v[124:127]
	v_mfma_f32_16x16x32_bf16 v[120:123], v[160:163], v[184:187], v[120:123]
	v_mfma_f32_16x16x32_bf16 v[108:111], v[144:147], v[192:195], v[108:111]
	v_mfma_f32_16x16x32_bf16 v[104:107], v[160:163], v[192:195], v[104:107]
	v_mfma_f32_16x16x32_bf16 v[92:95], v[144:147], v[200:203], v[92:95]
	v_mfma_f32_16x16x32_bf16 v[88:91], v[160:163], v[200:203], v[88:91]
	v_mfma_f32_16x16x32_bf16 v[76:79], v[144:147], v[208:211], v[76:79]
	v_mfma_f32_16x16x32_bf16 v[72:75], v[160:163], v[208:211], v[72:75]
	v_mfma_f32_16x16x32_bf16 v[124:127], v[156:159], v[188:191], v[124:127]
	v_mfma_f32_16x16x32_bf16 v[120:123], v[164:167], v[188:191], v[120:123]
	v_mfma_f32_16x16x32_bf16 v[108:111], v[156:159], v[196:199], v[108:111]
	v_mfma_f32_16x16x32_bf16 v[104:107], v[164:167], v[196:199], v[104:107]
	v_mfma_f32_16x16x32_bf16 v[92:95], v[156:159], v[204:207], v[92:95]
	v_mfma_f32_16x16x32_bf16 v[88:91], v[164:167], v[204:207], v[88:91]
	v_mfma_f32_16x16x32_bf16 v[76:79], v[156:159], v[216:219], v[76:79]
	v_mfma_f32_16x16x32_bf16 v[72:75], v[164:167], v[216:219], v[72:75]
	s_setprio 0
	s_setprio 1
	v_mfma_f32_16x16x32_bf16 v[116:119], v[168:171], v[184:187], v[116:119]
	v_mfma_f32_16x16x32_bf16 v[112:115], v[176:179], v[184:187], v[112:115]
	v_mfma_f32_16x16x32_bf16 v[100:103], v[168:171], v[192:195], v[100:103]
	v_mfma_f32_16x16x32_bf16 v[96:99], v[176:179], v[192:195], v[96:99]
	v_mfma_f32_16x16x32_bf16 v[84:87], v[168:171], v[200:203], v[84:87]
	v_mfma_f32_16x16x32_bf16 v[80:83], v[176:179], v[200:203], v[80:83]
	v_mfma_f32_16x16x32_bf16 v[68:71], v[168:171], v[208:211], v[68:71]
	v_mfma_f32_16x16x32_bf16 v[64:67], v[176:179], v[208:211], v[64:67]
	v_mfma_f32_16x16x32_bf16 v[116:119], v[172:175], v[188:191], v[116:119]
	v_mfma_f32_16x16x32_bf16 v[112:115], v[180:183], v[188:191], v[112:115]
	v_mfma_f32_16x16x32_bf16 v[100:103], v[172:175], v[196:199], v[100:103]
	v_mfma_f32_16x16x32_bf16 v[96:99], v[180:183], v[196:199], v[96:99]
	v_mfma_f32_16x16x32_bf16 v[84:87], v[172:175], v[204:207], v[84:87]
	v_mfma_f32_16x16x32_bf16 v[80:83], v[180:183], v[204:207], v[80:83]
	v_mfma_f32_16x16x32_bf16 v[68:71], v[172:175], v[216:219], v[68:71]
	v_mfma_f32_16x16x32_bf16 v[64:67], v[180:183], v[216:219], v[64:67]
	s_setprio 0
	s_barrier
	s_add_i32 s28, s63, s18
	s_mov_b32 m0, s28
	ds_read_b128 v[184:187], v155 offset:16384
	ds_read_b128 v[188:191], v155 offset:17408
	ds_read_b128 v[192:195], v155 offset:18432
	ds_read_b128 v[196:199], v155 offset:19456
	ds_read_b128 v[200:203], v155 offset:20480
	ds_read_b128 v[204:207], v155 offset:21504
	ds_read_b128 v[208:211], v155 offset:22528
	ds_read_b128 v[216:219], v155 offset:23552
	global_load_lds_dwordx4 v130, s[54:55]
	s_add_i32 m0, s28, 0x2000
	s_add_u32 s28, s54, 0x40000
	s_addc_u32 s29, s55, 0
	s_add_i32 s30, s64, s18
	global_load_lds_dwordx4 v134, s[54:55]
	s_mov_b32 m0, s30
	s_nop 0
	global_load_lds_dwordx4 v130, s[28:29]
	s_add_i32 m0, s30, 0x2000
	s_nop 0
	global_load_lds_dwordx4 v134, s[28:29]
	s_mov_b32 m0, s19
	s_nop 0
	global_load_lds_dwordx4 v128, s[56:57]
	s_mov_b32 m0, s20
	s_nop 0
	global_load_lds_dwordx4 v132, s[56:57]
	s_waitcnt vmcnt(8)
	s_waitcnt lgkmcnt(0)
	s_barrier
	s_setprio 1
	s_waitcnt lgkmcnt(0)
	v_mfma_f32_16x16x32_bf16 v[60:63], v[144:147], v[184:187], v[60:63]
	v_mfma_f32_16x16x32_bf16 v[56:59], v[160:163], v[184:187], v[56:59]
	v_mfma_f32_16x16x32_bf16 v[44:47], v[144:147], v[192:195], v[44:47]
	v_mfma_f32_16x16x32_bf16 v[40:43], v[160:163], v[192:195], v[40:43]
	v_mfma_f32_16x16x32_bf16 v[28:31], v[144:147], v[200:203], v[28:31]
	v_mfma_f32_16x16x32_bf16 v[24:27], v[160:163], v[200:203], v[24:27]
	v_mfma_f32_16x16x32_bf16 v[12:15], v[144:147], v[208:211], v[12:15]
	v_mfma_f32_16x16x32_bf16 v[8:11], v[160:163], v[208:211], v[8:11]
	v_mfma_f32_16x16x32_bf16 v[60:63], v[156:159], v[188:191], v[60:63]
	v_mfma_f32_16x16x32_bf16 v[56:59], v[164:167], v[188:191], v[56:59]
	v_mfma_f32_16x16x32_bf16 v[44:47], v[156:159], v[196:199], v[44:47]
	v_mfma_f32_16x16x32_bf16 v[40:43], v[164:167], v[196:199], v[40:43]
	v_mfma_f32_16x16x32_bf16 v[28:31], v[156:159], v[204:207], v[28:31]
	v_mfma_f32_16x16x32_bf16 v[24:27], v[164:167], v[204:207], v[24:27]
	v_mfma_f32_16x16x32_bf16 v[12:15], v[156:159], v[216:219], v[12:15]
	v_mfma_f32_16x16x32_bf16 v[8:11], v[164:167], v[216:219], v[8:11]
	s_setprio 0
	s_setprio 1
	v_mfma_f32_16x16x32_bf16 v[52:55], v[168:171], v[184:187], v[52:55]
	v_mfma_f32_16x16x32_bf16 v[48:51], v[176:179], v[184:187], v[48:51]
	v_mfma_f32_16x16x32_bf16 v[36:39], v[168:171], v[192:195], v[36:39]
	v_mfma_f32_16x16x32_bf16 v[32:35], v[176:179], v[192:195], v[32:35]
	v_mfma_f32_16x16x32_bf16 v[20:23], v[168:171], v[200:203], v[20:23]
	v_mfma_f32_16x16x32_bf16 v[16:19], v[176:179], v[200:203], v[16:19]
	v_mfma_f32_16x16x32_bf16 v[4:7], v[168:171], v[208:211], v[4:7]
	v_mfma_f32_16x16x32_bf16 v[0:3], v[176:179], v[208:211], v[0:3]
	v_mfma_f32_16x16x32_bf16 v[52:55], v[172:175], v[188:191], v[52:55]
	v_mfma_f32_16x16x32_bf16 v[48:51], v[180:183], v[188:191], v[48:51]
	v_mfma_f32_16x16x32_bf16 v[36:39], v[172:175], v[196:199], v[36:39]
	v_mfma_f32_16x16x32_bf16 v[32:35], v[180:183], v[196:199], v[32:35]
	v_mfma_f32_16x16x32_bf16 v[20:23], v[172:175], v[204:207], v[20:23]
	v_mfma_f32_16x16x32_bf16 v[16:19], v[180:183], v[204:207], v[16:19]
	v_mfma_f32_16x16x32_bf16 v[4:7], v[172:175], v[216:219], v[4:7]
	v_mfma_f32_16x16x32_bf16 v[0:3], v[180:183], v[216:219], v[0:3]
	s_setprio 0
	s_barrier
	s_add_i32 s30, 0, 0x18000
	s_add_i32 s31, 0, 0x1c000
	v_add_u32_e32 v164, s30, v151
	v_add_u32_e32 v180, s31, v151
	ds_read_b128 v[144:147], v164
	ds_read_b128 v[156:159], v164 offset:1024
	ds_read_b128 v[160:163], v164 offset:2048
	ds_read_b128 v[164:167], v164 offset:3072
	ds_read_b128 v[168:171], v180
	ds_read_b128 v[172:175], v180 offset:1024
	ds_read_b128 v[176:179], v180 offset:2048
	ds_read_b128 v[180:183], v180 offset:3072
	s_add_u32 s28, s56, 0x40000
	s_addc_u32 s29, s57, 0
	s_mov_b32 m0, s21
	ds_read_b128 v[184:187], v155 offset:32768
	ds_read_b128 v[188:191], v155 offset:33792
	ds_read_b128 v[192:195], v155 offset:34816
	ds_read_b128 v[196:199], v155 offset:35840
	ds_read_b128 v[200:203], v155 offset:36864
	ds_read_b128 v[204:207], v155 offset:37888
	ds_read_b128 v[208:211], v155 offset:38912
	ds_read_b128 v[216:219], v155 offset:39936
	global_load_lds_dwordx4 v128, s[28:29]
	s_mov_b32 m0, s22
	s_nop 0
	global_load_lds_dwordx4 v132, s[28:29]
	s_waitcnt vmcnt(8)
	s_waitcnt lgkmcnt(0)
	s_barrier
	s_setprio 1
	s_waitcnt lgkmcnt(0)
	v_mfma_f32_16x16x32_bf16 v[124:127], v[144:147], v[184:187], v[124:127]
	v_mfma_f32_16x16x32_bf16 v[120:123], v[160:163], v[184:187], v[120:123]
	v_mfma_f32_16x16x32_bf16 v[108:111], v[144:147], v[192:195], v[108:111]
	v_mfma_f32_16x16x32_bf16 v[104:107], v[160:163], v[192:195], v[104:107]
	v_mfma_f32_16x16x32_bf16 v[92:95], v[144:147], v[200:203], v[92:95]
	v_mfma_f32_16x16x32_bf16 v[88:91], v[160:163], v[200:203], v[88:91]
	v_mfma_f32_16x16x32_bf16 v[76:79], v[144:147], v[208:211], v[76:79]
	v_mfma_f32_16x16x32_bf16 v[72:75], v[160:163], v[208:211], v[72:75]
	v_mfma_f32_16x16x32_bf16 v[124:127], v[156:159], v[188:191], v[124:127]
	v_mfma_f32_16x16x32_bf16 v[120:123], v[164:167], v[188:191], v[120:123]
	v_mfma_f32_16x16x32_bf16 v[108:111], v[156:159], v[196:199], v[108:111]
	v_mfma_f32_16x16x32_bf16 v[104:107], v[164:167], v[196:199], v[104:107]
	v_mfma_f32_16x16x32_bf16 v[92:95], v[156:159], v[204:207], v[92:95]
	v_mfma_f32_16x16x32_bf16 v[88:91], v[164:167], v[204:207], v[88:91]
	v_mfma_f32_16x16x32_bf16 v[76:79], v[156:159], v[216:219], v[76:79]
	v_mfma_f32_16x16x32_bf16 v[72:75], v[164:167], v[216:219], v[72:75]
	s_setprio 0
	s_setprio 1
	v_mfma_f32_16x16x32_bf16 v[116:119], v[168:171], v[184:187], v[116:119]
	v_mfma_f32_16x16x32_bf16 v[112:115], v[176:179], v[184:187], v[112:115]
	v_mfma_f32_16x16x32_bf16 v[100:103], v[168:171], v[192:195], v[100:103]
	v_mfma_f32_16x16x32_bf16 v[96:99], v[176:179], v[192:195], v[96:99]
	v_mfma_f32_16x16x32_bf16 v[84:87], v[168:171], v[200:203], v[84:87]
	v_mfma_f32_16x16x32_bf16 v[80:83], v[176:179], v[200:203], v[80:83]
	v_mfma_f32_16x16x32_bf16 v[68:71], v[168:171], v[208:211], v[68:71]
	v_mfma_f32_16x16x32_bf16 v[64:67], v[176:179], v[208:211], v[64:67]
	v_mfma_f32_16x16x32_bf16 v[116:119], v[172:175], v[188:191], v[116:119]
	v_mfma_f32_16x16x32_bf16 v[112:115], v[180:183], v[188:191], v[112:115]
	v_mfma_f32_16x16x32_bf16 v[100:103], v[172:175], v[196:199], v[100:103]
	v_mfma_f32_16x16x32_bf16 v[96:99], v[180:183], v[196:199], v[96:99]
	v_mfma_f32_16x16x32_bf16 v[84:87], v[172:175], v[204:207], v[84:87]
	v_mfma_f32_16x16x32_bf16 v[80:83], v[180:183], v[204:207], v[80:83]
	v_mfma_f32_16x16x32_bf16 v[68:71], v[172:175], v[216:219], v[68:71]
	v_mfma_f32_16x16x32_bf16 v[64:67], v[180:183], v[216:219], v[64:67]
	s_setprio 0
	s_barrier
	s_add_i32 m0, s30, s18
	s_add_u32 s28, s54, 0x80
	s_addc_u32 s29, s55, 0
	ds_read_b128 v[184:187], v155 offset:49152
	ds_read_b128 v[188:191], v155 offset:50176
	ds_read_b128 v[192:195], v155 offset:51200
	ds_read_b128 v[196:199], v155 offset:52224
	ds_read_b128 v[200:203], v155 offset:53248
	ds_read_b128 v[204:207], v155 offset:54272
	ds_read_b128 v[208:211], v155 offset:55296
	ds_read_b128 v[216:219], v155 offset:56320
	global_load_lds_dwordx4 v130, s[28:29]
	s_add_i32 m0, m0, 0x2000
	s_add_i32 s30, s31, s18
	global_load_lds_dwordx4 v134, s[28:29]
	s_add_u32 s28, s28, 0x40000
	s_addc_u32 s29, s29, 0
	s_mov_b32 m0, s30
	s_nop 0
	global_load_lds_dwordx4 v130, s[28:29]
	s_add_i32 m0, s30, 0x2000
	s_nop 0
	global_load_lds_dwordx4 v134, s[28:29]
	s_add_u32 s28, s56, 0x80
	s_addc_u32 s29, s57, 0
	s_mov_b32 m0, s33
	s_nop 0
	global_load_lds_dwordx4 v128, s[28:29]
	s_mov_b32 m0, s58
	s_nop 0
	global_load_lds_dwordx4 v132, s[28:29]
	s_add_u32 s28, s54, 0x40080
	s_addc_u32 s29, s55, 0
	s_waitcnt vmcnt(8)
	s_waitcnt lgkmcnt(0)
	s_barrier
	s_setprio 1
	s_waitcnt lgkmcnt(0)
	v_mfma_f32_16x16x32_bf16 v[60:63], v[144:147], v[184:187], v[60:63]
	v_mfma_f32_16x16x32_bf16 v[56:59], v[160:163], v[184:187], v[56:59]
	v_mfma_f32_16x16x32_bf16 v[44:47], v[144:147], v[192:195], v[44:47]
	v_mfma_f32_16x16x32_bf16 v[40:43], v[160:163], v[192:195], v[40:43]
	v_mfma_f32_16x16x32_bf16 v[28:31], v[144:147], v[200:203], v[28:31]
	v_mfma_f32_16x16x32_bf16 v[24:27], v[160:163], v[200:203], v[24:27]
	v_mfma_f32_16x16x32_bf16 v[12:15], v[144:147], v[208:211], v[12:15]
	v_mfma_f32_16x16x32_bf16 v[8:11], v[160:163], v[208:211], v[8:11]
	v_mfma_f32_16x16x32_bf16 v[60:63], v[156:159], v[188:191], v[60:63]
	v_mfma_f32_16x16x32_bf16 v[56:59], v[164:167], v[188:191], v[56:59]
	v_mfma_f32_16x16x32_bf16 v[44:47], v[156:159], v[196:199], v[44:47]
	v_mfma_f32_16x16x32_bf16 v[40:43], v[164:167], v[196:199], v[40:43]
	v_mfma_f32_16x16x32_bf16 v[28:31], v[156:159], v[204:207], v[28:31]
	v_mfma_f32_16x16x32_bf16 v[24:27], v[164:167], v[204:207], v[24:27]
	v_mfma_f32_16x16x32_bf16 v[12:15], v[156:159], v[216:219], v[12:15]
	v_mfma_f32_16x16x32_bf16 v[8:11], v[164:167], v[216:219], v[8:11]
	s_setprio 0
	s_setprio 1
	v_mfma_f32_16x16x32_bf16 v[52:55], v[168:171], v[184:187], v[52:55]
	v_mfma_f32_16x16x32_bf16 v[48:51], v[176:179], v[184:187], v[48:51]
	v_mfma_f32_16x16x32_bf16 v[36:39], v[168:171], v[192:195], v[36:39]
	v_mfma_f32_16x16x32_bf16 v[32:35], v[176:179], v[192:195], v[32:35]
	v_mfma_f32_16x16x32_bf16 v[20:23], v[168:171], v[200:203], v[20:23]
	v_mfma_f32_16x16x32_bf16 v[16:19], v[176:179], v[200:203], v[16:19]
	v_mfma_f32_16x16x32_bf16 v[4:7], v[168:171], v[208:211], v[4:7]
	v_mfma_f32_16x16x32_bf16 v[0:3], v[176:179], v[208:211], v[0:3]
	v_mfma_f32_16x16x32_bf16 v[52:55], v[172:175], v[188:191], v[52:55]
	v_mfma_f32_16x16x32_bf16 v[48:51], v[180:183], v[188:191], v[48:51]
	v_mfma_f32_16x16x32_bf16 v[36:39], v[172:175], v[196:199], v[36:39]
	v_mfma_f32_16x16x32_bf16 v[32:35], v[180:183], v[196:199], v[32:35]
	v_mfma_f32_16x16x32_bf16 v[20:23], v[172:175], v[204:207], v[20:23]
	v_mfma_f32_16x16x32_bf16 v[16:19], v[180:183], v[204:207], v[16:19]
	v_mfma_f32_16x16x32_bf16 v[4:7], v[172:175], v[216:219], v[4:7]
	v_mfma_f32_16x16x32_bf16 v[0:3], v[180:183], v[216:219], v[0:3]
	s_setprio 0
	s_barrier
	s_add_i32 s27, s27, 2
	s_add_u32 s12, s12, 0x100
	s_addc_u32 s13, s13, 0
	s_add_u32 s25, s25, 0x100
	s_addc_u32 s26, s26, 0
	s_cmp_gt_u32 s27, 13
	s_cbranch_scc0 .LBB0_640
	s_and_b64 vcc, exec, s[8:9]
	s_cbranch_vccz .LBB0_643
	s_barrier

.LBB0_744:
	ds_read_b128 v[80:83], v226
	ds_read_b128 v[84:87], v226 offset:1024
	ds_read_b128 v[88:91], v226 offset:2048
	ds_read_b128 v[92:95], v226 offset:3072
	ds_read_b128 v[128:131], v227
	ds_read_b128 v[132:135], v227 offset:1024
	ds_read_b128 v[152:155], v227 offset:2048
	ds_read_b128 v[156:159], v227 offset:3072
	s_add_u32 s26, s46, 0xfffc0080
	s_addc_u32 s27, s47, -1
	s_cmp_eq_u32 s25, 12
	s_cselect_b32 s89, s11, s27
	s_cselect_b32 s88, s14, s26
	s_cselect_b32 s49, s15, s24
	s_cselect_b32 s48, s16, s17
	s_add_i32 m0, s13, 0xc000
	ds_read_b128 v[160:163], v228
	ds_read_b128 v[164:167], v228 offset:1024
	ds_read_b128 v[168:171], v228 offset:2048
	ds_read_b128 v[172:175], v228 offset:3072
	ds_read_b128 v[192:195], v228 offset:4096
	ds_read_b128 v[196:199], v228 offset:5120
	ds_read_b128 v[200:203], v228 offset:6144
	ds_read_b128 v[204:207], v228 offset:7168
	global_load_lds_dwordx4 v184, s[46:47]
	s_add_i32 m0, s13, 0xe000
	s_nop 0
	global_load_lds_dwordx4 v186, s[46:47]
	s_waitcnt vmcnt(8)
	s_waitcnt lgkmcnt(0)
	s_barrier
	s_setprio 1
	s_waitcnt lgkmcnt(0)
	v_mfma_f32_16x16x32_bf16 v[76:79], v[80:83], v[160:163], v[76:79]
	v_mfma_f32_16x16x32_bf16 v[64:67], v[88:91], v[160:163], v[64:67]
	v_mfma_f32_16x16x32_bf16 v[148:151], v[80:83], v[168:171], v[148:151]
	v_mfma_f32_16x16x32_bf16 v[140:143], v[88:91], v[168:171], v[140:143]
	v_mfma_f32_16x16x32_bf16 v[124:127], v[80:83], v[192:195], v[124:127]
	v_mfma_f32_16x16x32_bf16 v[120:123], v[88:91], v[192:195], v[120:123]
	v_mfma_f32_16x16x32_bf16 v[72:75], v[80:83], v[200:203], v[72:75]
	v_mfma_f32_16x16x32_bf16 v[60:63], v[88:91], v[200:203], v[60:63]
	v_mfma_f32_16x16x32_bf16 v[76:79], v[84:87], v[164:167], v[76:79]
	v_mfma_f32_16x16x32_bf16 v[64:67], v[92:95], v[164:167], v[64:67]
	v_mfma_f32_16x16x32_bf16 v[148:151], v[84:87], v[172:175], v[148:151]
	v_mfma_f32_16x16x32_bf16 v[140:143], v[92:95], v[172:175], v[140:143]
	v_mfma_f32_16x16x32_bf16 v[124:127], v[84:87], v[196:199], v[124:127]
	v_mfma_f32_16x16x32_bf16 v[120:123], v[92:95], v[196:199], v[120:123]
	v_mfma_f32_16x16x32_bf16 v[72:75], v[84:87], v[204:207], v[72:75]
	v_mfma_f32_16x16x32_bf16 v[60:63], v[92:95], v[204:207], v[60:63]
	s_setprio 0
	s_setprio 1
	v_mfma_f32_16x16x32_bf16 v[144:147], v[128:131], v[160:163], v[144:147]
	v_mfma_f32_16x16x32_bf16 v[136:139], v[152:155], v[160:163], v[136:139]
	v_mfma_f32_16x16x32_bf16 v[116:119], v[128:131], v[168:171], v[116:119]
	v_mfma_f32_16x16x32_bf16 v[112:115], v[152:155], v[168:171], v[112:115]
	v_mfma_f32_16x16x32_bf16 v[108:111], v[128:131], v[192:195], v[108:111]
	v_mfma_f32_16x16x32_bf16 v[104:107], v[152:155], v[192:195], v[104:107]
	v_mfma_f32_16x16x32_bf16 v[100:103], v[128:131], v[200:203], v[100:103]
	v_mfma_f32_16x16x32_bf16 v[96:99], v[152:155], v[200:203], v[96:99]
	v_mfma_f32_16x16x32_bf16 v[144:147], v[132:135], v[164:167], v[144:147]
	v_mfma_f32_16x16x32_bf16 v[136:139], v[156:159], v[164:167], v[136:139]
	v_mfma_f32_16x16x32_bf16 v[116:119], v[132:135], v[172:175], v[116:119]
	v_mfma_f32_16x16x32_bf16 v[112:115], v[156:159], v[172:175], v[112:115]
	v_mfma_f32_16x16x32_bf16 v[108:111], v[132:135], v[196:199], v[108:111]
	v_mfma_f32_16x16x32_bf16 v[104:107], v[156:159], v[196:199], v[104:107]
	v_mfma_f32_16x16x32_bf16 v[100:103], v[132:135], v[204:207], v[100:103]
	v_mfma_f32_16x16x32_bf16 v[96:99], v[156:159], v[204:207], v[96:99]
	s_setprio 0
	s_barrier
	s_add_i32 s26, s3, s20
	s_mov_b32 m0, s26
	ds_read_b128 v[160:163], v228 offset:16384
	ds_read_b128 v[164:167], v228 offset:17408
	ds_read_b128 v[168:171], v228 offset:18432
	ds_read_b128 v[172:175], v228 offset:19456
	ds_read_b128 v[192:195], v228 offset:20480
	ds_read_b128 v[196:199], v228 offset:21504
	ds_read_b128 v[200:203], v228 offset:22528
	ds_read_b128 v[204:207], v228 offset:23552
	global_load_lds_dwordx4 v178, s[48:49]
	s_add_i32 m0, s26, 0x2000
	s_add_u32 s26, s48, 0x40000
	s_addc_u32 s27, s49, 0
	s_add_i32 s28, s93, s20
	global_load_lds_dwordx4 v182, s[48:49]
	s_mov_b32 m0, s28
	s_nop 0
	global_load_lds_dwordx4 v178, s[26:27]
	s_add_i32 m0, s28, 0x2000
	s_nop 0
	global_load_lds_dwordx4 v182, s[26:27]
	s_mov_b32 m0, s13
	s_nop 0
	global_load_lds_dwordx4 v176, s[88:89]
	s_mov_b32 m0, s21
	s_nop 0
	global_load_lds_dwordx4 v180, s[88:89]
	s_waitcnt vmcnt(8)
	s_waitcnt lgkmcnt(0)
	s_barrier
	s_setprio 1
	s_waitcnt lgkmcnt(0)
	v_mfma_f32_16x16x32_bf16 v[68:71], v[80:83], v[160:163], v[68:71]
	v_mfma_f32_16x16x32_bf16 v[36:39], v[88:91], v[160:163], v[36:39]
	v_mfma_f32_16x16x32_bf16 v[52:55], v[80:83], v[168:171], v[52:55]
	v_mfma_f32_16x16x32_bf16 v[44:47], v[88:91], v[168:171], v[44:47]
	v_mfma_f32_16x16x32_bf16 v[28:31], v[80:83], v[192:195], v[28:31]
	v_mfma_f32_16x16x32_bf16 v[24:27], v[88:91], v[192:195], v[24:27]
	v_mfma_f32_16x16x32_bf16 v[56:59], v[80:83], v[200:203], v[56:59]
	v_mfma_f32_16x16x32_bf16 v[32:35], v[88:91], v[200:203], v[32:35]
	v_mfma_f32_16x16x32_bf16 v[68:71], v[84:87], v[164:167], v[68:71]
	v_mfma_f32_16x16x32_bf16 v[36:39], v[92:95], v[164:167], v[36:39]
	v_mfma_f32_16x16x32_bf16 v[52:55], v[84:87], v[172:175], v[52:55]
	v_mfma_f32_16x16x32_bf16 v[44:47], v[92:95], v[172:175], v[44:47]
	v_mfma_f32_16x16x32_bf16 v[28:31], v[84:87], v[196:199], v[28:31]
	v_mfma_f32_16x16x32_bf16 v[24:27], v[92:95], v[196:199], v[24:27]
	v_mfma_f32_16x16x32_bf16 v[56:59], v[84:87], v[204:207], v[56:59]
	v_mfma_f32_16x16x32_bf16 v[32:35], v[92:95], v[204:207], v[32:35]
	s_setprio 0
	s_setprio 1
	v_mfma_f32_16x16x32_bf16 v[48:51], v[128:131], v[160:163], v[48:51]
	v_mfma_f32_16x16x32_bf16 v[40:43], v[152:155], v[160:163], v[40:43]
	v_mfma_f32_16x16x32_bf16 v[20:23], v[128:131], v[168:171], v[20:23]
	v_mfma_f32_16x16x32_bf16 v[16:19], v[152:155], v[168:171], v[16:19]
	v_mfma_f32_16x16x32_bf16 v[12:15], v[128:131], v[192:195], v[12:15]
	v_mfma_f32_16x16x32_bf16 v[8:11], v[152:155], v[192:195], v[8:11]
	v_mfma_f32_16x16x32_bf16 v[4:7], v[128:131], v[200:203], v[4:7]
	v_mfma_f32_16x16x32_bf16 v[0:3], v[152:155], v[200:203], v[0:3]
	v_mfma_f32_16x16x32_bf16 v[48:51], v[132:135], v[164:167], v[48:51]
	v_mfma_f32_16x16x32_bf16 v[40:43], v[156:159], v[164:167], v[40:43]
	v_mfma_f32_16x16x32_bf16 v[20:23], v[132:135], v[172:175], v[20:23]
	v_mfma_f32_16x16x32_bf16 v[16:19], v[156:159], v[172:175], v[16:19]
	v_mfma_f32_16x16x32_bf16 v[12:15], v[132:135], v[196:199], v[12:15]
	v_mfma_f32_16x16x32_bf16 v[8:11], v[156:159], v[196:199], v[8:11]
	v_mfma_f32_16x16x32_bf16 v[4:7], v[132:135], v[204:207], v[4:7]
	v_mfma_f32_16x16x32_bf16 v[0:3], v[156:159], v[204:207], v[0:3]
	s_setprio 0
	s_barrier
	s_add_i32 s28, 0, 0x18000
	s_add_i32 s29, 0, 0x1c000
	v_add_u32_e32 v92, s28, v218
	v_add_u32_e32 v156, s29, v218
	ds_read_b128 v[80:83], v92
	ds_read_b128 v[84:87], v92 offset:1024
	ds_read_b128 v[88:91], v92 offset:2048
	ds_read_b128 v[92:95], v92 offset:3072
	ds_read_b128 v[128:131], v156
	ds_read_b128 v[132:135], v156 offset:1024
	ds_read_b128 v[152:155], v156 offset:2048
	ds_read_b128 v[156:159], v156 offset:3072
	s_add_u32 s26, s88, 0x40000
	s_addc_u32 s27, s89, 0
	s_mov_b32 m0, s22
	ds_read_b128 v[160:163], v228 offset:32768
	ds_read_b128 v[164:167], v228 offset:33792
	ds_read_b128 v[168:171], v228 offset:34816
	ds_read_b128 v[172:175], v228 offset:35840
	ds_read_b128 v[192:195], v228 offset:36864
	ds_read_b128 v[196:199], v228 offset:37888
	ds_read_b128 v[200:203], v228 offset:38912
	ds_read_b128 v[204:207], v228 offset:39936
	global_load_lds_dwordx4 v176, s[26:27]
	s_mov_b32 m0, s23
	s_nop 0
	global_load_lds_dwordx4 v180, s[26:27]
	s_waitcnt vmcnt(8)
	s_waitcnt lgkmcnt(0)
	s_barrier
	s_setprio 1
	s_waitcnt lgkmcnt(0)
	v_mfma_f32_16x16x32_bf16 v[76:79], v[80:83], v[160:163], v[76:79]
	v_mfma_f32_16x16x32_bf16 v[64:67], v[88:91], v[160:163], v[64:67]
	v_mfma_f32_16x16x32_bf16 v[148:151], v[80:83], v[168:171], v[148:151]
	v_mfma_f32_16x16x32_bf16 v[140:143], v[88:91], v[168:171], v[140:143]
	v_mfma_f32_16x16x32_bf16 v[124:127], v[80:83], v[192:195], v[124:127]
	v_mfma_f32_16x16x32_bf16 v[120:123], v[88:91], v[192:195], v[120:123]
	v_mfma_f32_16x16x32_bf16 v[72:75], v[80:83], v[200:203], v[72:75]
	v_mfma_f32_16x16x32_bf16 v[60:63], v[88:91], v[200:203], v[60:63]
	v_mfma_f32_16x16x32_bf16 v[76:79], v[84:87], v[164:167], v[76:79]
	v_mfma_f32_16x16x32_bf16 v[64:67], v[92:95], v[164:167], v[64:67]
	v_mfma_f32_16x16x32_bf16 v[148:151], v[84:87], v[172:175], v[148:151]
	v_mfma_f32_16x16x32_bf16 v[140:143], v[92:95], v[172:175], v[140:143]
	v_mfma_f32_16x16x32_bf16 v[124:127], v[84:87], v[196:199], v[124:127]
	v_mfma_f32_16x16x32_bf16 v[120:123], v[92:95], v[196:199], v[120:123]
	v_mfma_f32_16x16x32_bf16 v[72:75], v[84:87], v[204:207], v[72:75]
	v_mfma_f32_16x16x32_bf16 v[60:63], v[92:95], v[204:207], v[60:63]
	s_setprio 0
	s_setprio 1
	v_mfma_f32_16x16x32_bf16 v[144:147], v[128:131], v[160:163], v[144:147]
	v_mfma_f32_16x16x32_bf16 v[136:139], v[152:155], v[160:163], v[136:139]
	v_mfma_f32_16x16x32_bf16 v[116:119], v[128:131], v[168:171], v[116:119]
	v_mfma_f32_16x16x32_bf16 v[112:115], v[152:155], v[168:171], v[112:115]
	v_mfma_f32_16x16x32_bf16 v[108:111], v[128:131], v[192:195], v[108:111]
	v_mfma_f32_16x16x32_bf16 v[104:107], v[152:155], v[192:195], v[104:107]
	v_mfma_f32_16x16x32_bf16 v[100:103], v[128:131], v[200:203], v[100:103]
	v_mfma_f32_16x16x32_bf16 v[96:99], v[152:155], v[200:203], v[96:99]
	v_mfma_f32_16x16x32_bf16 v[144:147], v[132:135], v[164:167], v[144:147]
	v_mfma_f32_16x16x32_bf16 v[136:139], v[156:159], v[164:167], v[136:139]
	v_mfma_f32_16x16x32_bf16 v[116:119], v[132:135], v[172:175], v[116:119]
	v_mfma_f32_16x16x32_bf16 v[112:115], v[156:159], v[172:175], v[112:115]
	v_mfma_f32_16x16x32_bf16 v[108:111], v[132:135], v[196:199], v[108:111]
	v_mfma_f32_16x16x32_bf16 v[104:107], v[156:159], v[196:199], v[104:107]
	v_mfma_f32_16x16x32_bf16 v[100:103], v[132:135], v[204:207], v[100:103]
	v_mfma_f32_16x16x32_bf16 v[96:99], v[156:159], v[204:207], v[96:99]
	s_setprio 0
	s_barrier
	s_add_i32 m0, s28, s20
	s_add_u32 s26, s48, 0x80
	s_addc_u32 s27, s49, 0
	ds_read_b128 v[160:163], v228 offset:49152
	ds_read_b128 v[164:167], v228 offset:50176
	ds_read_b128 v[168:171], v228 offset:51200
	ds_read_b128 v[172:175], v228 offset:52224
	ds_read_b128 v[192:195], v228 offset:53248
	ds_read_b128 v[196:199], v228 offset:54272
	ds_read_b128 v[200:203], v228 offset:55296
	ds_read_b128 v[204:207], v228 offset:56320
	global_load_lds_dwordx4 v178, s[26:27]
	s_add_i32 m0, m0, 0x2000
	s_add_i32 s28, s29, s20
	global_load_lds_dwordx4 v182, s[26:27]
	s_add_u32 s26, s26, 0x40000
	s_addc_u32 s27, s27, 0
	s_mov_b32 m0, s28
	s_nop 0
	global_load_lds_dwordx4 v178, s[26:27]
	s_add_i32 m0, s28, 0x2000
	s_nop 0
	global_load_lds_dwordx4 v182, s[26:27]
	s_add_u32 s26, s88, 0x80
	s_addc_u32 s27, s89, 0
	s_mov_b32 m0, s71
	s_nop 0
	global_load_lds_dwordx4 v176, s[26:27]
	s_mov_b32 m0, s73
	s_nop 0
	global_load_lds_dwordx4 v180, s[26:27]
	s_add_u32 s26, s48, 0x40080
	s_addc_u32 s27, s49, 0
	s_waitcnt vmcnt(8)
	s_waitcnt lgkmcnt(0)
	s_barrier
	s_setprio 1
	s_waitcnt lgkmcnt(0)
	v_mfma_f32_16x16x32_bf16 v[68:71], v[80:83], v[160:163], v[68:71]
	v_mfma_f32_16x16x32_bf16 v[36:39], v[88:91], v[160:163], v[36:39]
	v_mfma_f32_16x16x32_bf16 v[52:55], v[80:83], v[168:171], v[52:55]
	v_mfma_f32_16x16x32_bf16 v[44:47], v[88:91], v[168:171], v[44:47]
	v_mfma_f32_16x16x32_bf16 v[28:31], v[80:83], v[192:195], v[28:31]
	v_mfma_f32_16x16x32_bf16 v[24:27], v[88:91], v[192:195], v[24:27]
	v_mfma_f32_16x16x32_bf16 v[56:59], v[80:83], v[200:203], v[56:59]
	v_mfma_f32_16x16x32_bf16 v[32:35], v[88:91], v[200:203], v[32:35]
	v_mfma_f32_16x16x32_bf16 v[68:71], v[84:87], v[164:167], v[68:71]
	v_mfma_f32_16x16x32_bf16 v[36:39], v[92:95], v[164:167], v[36:39]
	v_mfma_f32_16x16x32_bf16 v[52:55], v[84:87], v[172:175], v[52:55]
	v_mfma_f32_16x16x32_bf16 v[44:47], v[92:95], v[172:175], v[44:47]
	v_mfma_f32_16x16x32_bf16 v[28:31], v[84:87], v[196:199], v[28:31]
	v_mfma_f32_16x16x32_bf16 v[24:27], v[92:95], v[196:199], v[24:27]
	v_mfma_f32_16x16x32_bf16 v[56:59], v[84:87], v[204:207], v[56:59]
	v_mfma_f32_16x16x32_bf16 v[32:35], v[92:95], v[204:207], v[32:35]
	s_setprio 0
	s_setprio 1
	v_mfma_f32_16x16x32_bf16 v[48:51], v[128:131], v[160:163], v[48:51]
	v_mfma_f32_16x16x32_bf16 v[40:43], v[152:155], v[160:163], v[40:43]
	v_mfma_f32_16x16x32_bf16 v[20:23], v[128:131], v[168:171], v[20:23]
	v_mfma_f32_16x16x32_bf16 v[16:19], v[152:155], v[168:171], v[16:19]
	v_mfma_f32_16x16x32_bf16 v[12:15], v[128:131], v[192:195], v[12:15]
	v_mfma_f32_16x16x32_bf16 v[8:11], v[152:155], v[192:195], v[8:11]
	v_mfma_f32_16x16x32_bf16 v[4:7], v[128:131], v[200:203], v[4:7]
	v_mfma_f32_16x16x32_bf16 v[0:3], v[152:155], v[200:203], v[0:3]
	v_mfma_f32_16x16x32_bf16 v[48:51], v[132:135], v[164:167], v[48:51]
	v_mfma_f32_16x16x32_bf16 v[40:43], v[156:159], v[164:167], v[40:43]
	v_mfma_f32_16x16x32_bf16 v[20:23], v[132:135], v[172:175], v[20:23]
	v_mfma_f32_16x16x32_bf16 v[16:19], v[156:159], v[172:175], v[16:19]
	v_mfma_f32_16x16x32_bf16 v[12:15], v[132:135], v[196:199], v[12:15]
	v_mfma_f32_16x16x32_bf16 v[8:11], v[156:159], v[196:199], v[8:11]
	v_mfma_f32_16x16x32_bf16 v[4:7], v[132:135], v[204:207], v[4:7]
	v_mfma_f32_16x16x32_bf16 v[0:3], v[156:159], v[204:207], v[0:3]
	s_setprio 0
	s_barrier
	s_add_i32 s25, s25, 2
	s_add_u32 s46, s46, 0x100
	s_addc_u32 s47, s47, 0
	s_add_u32 s17, s17, 0x100
	s_addc_u32 s24, s24, 0
	s_cmp_gt_u32 s25, 13
	s_cbranch_scc0 .LBB0_744
	v_mov_b32_e32 v80, v214
	s_movk_i32 s14, 0x100
	s_lshl_b32 s11, s10, 8
	s_nop 0
	v_cmp_gt_i32_e32 vcc, s14, v80
	s_and_saveexec_b64 s[46:47], vcc
	s_cbranch_execz .Lp8_noss
	v_add_u32_e32 v82, s11, v80
	v_ashrrev_i32_e32 v83, 31, v82
	v_lshlrev_b64 v[82:83], 6, v[82:83]
	v_lshl_add_u64 v[94:95], s[0:1], 0, v[82:83]
	global_load_dwordx4 v[82:85], v[94:95], off
	global_load_dwordx4 v[86:89], v[94:95], off offset:16
	global_load_dwordx4 v[90:93], v[94:95], off offset:32
	global_load_dwordx4 v[128:131], v[94:95], off offset:48

.LBB0_955:
	ds_read_b128 v[128:131], v197
	ds_read_b128 v[132:135], v197 offset:1024
	ds_read_b128 v[136:139], v197 offset:2048
	ds_read_b128 v[140:143], v197 offset:3072
	ds_read_b128 v[144:147], v198
	ds_read_b128 v[148:151], v198 offset:1024
	ds_read_b128 v[168:171], v198 offset:2048
	ds_read_b128 v[172:175], v198 offset:3072
	s_add_u32 s42, s44, 0x100
	s_addc_u32 s43, s45, 0
	s_cmp_eq_u32 s15, 40
	s_cselect_b32 s53, s9, s43
	s_cselect_b32 s52, s8, s42
	s_cselect_b32 s47, s11, s14
	s_cselect_b32 s46, s10, s13
	v_lshl_add_u64 v[176:177], s[44:45], 0, v[160:161]
	s_add_i32 m0, s18, 0xc000
	ds_read_b128 v[202:205], v199
	ds_read_b128 v[206:209], v199 offset:1024
	ds_read_b128 v[210:213], v199 offset:2048
	ds_read_b128 v[216:219], v199 offset:3072
	ds_read_b128 v[220:223], v199 offset:4096
	ds_read_b128 v[224:227], v199 offset:5120
	ds_read_b128 v[228:231], v199 offset:6144
	ds_read_b128 v[232:235], v199 offset:7168
	global_load_lds_dwordx4 v[176:177], off
	v_lshl_add_u64 v[176:177], s[44:45], 0, v[162:163]
	s_add_i32 m0, s18, 0xe000
	s_nop 0
	global_load_lds_dwordx4 v[176:177], off
	s_waitcnt vmcnt(8)
	s_waitcnt lgkmcnt(0)
	s_barrier
	s_setprio 1
	s_waitcnt lgkmcnt(0)
	v_mfma_f32_16x16x32_bf16 v[124:127], v[128:131], v[202:205], v[124:127]
	v_mfma_f32_16x16x32_bf16 v[120:123], v[136:139], v[202:205], v[120:123]
	v_mfma_f32_16x16x32_bf16 v[108:111], v[128:131], v[210:213], v[108:111]
	v_mfma_f32_16x16x32_bf16 v[104:107], v[136:139], v[210:213], v[104:107]
	v_mfma_f32_16x16x32_bf16 v[92:95], v[128:131], v[220:223], v[92:95]
	v_mfma_f32_16x16x32_bf16 v[88:91], v[136:139], v[220:223], v[88:91]
	v_mfma_f32_16x16x32_bf16 v[76:79], v[128:131], v[228:231], v[76:79]
	v_mfma_f32_16x16x32_bf16 v[72:75], v[136:139], v[228:231], v[72:75]
	v_mfma_f32_16x16x32_bf16 v[124:127], v[132:135], v[206:209], v[124:127]
	v_mfma_f32_16x16x32_bf16 v[120:123], v[140:143], v[206:209], v[120:123]
	v_mfma_f32_16x16x32_bf16 v[108:111], v[132:135], v[216:219], v[108:111]
	v_mfma_f32_16x16x32_bf16 v[104:107], v[140:143], v[216:219], v[104:107]
	v_mfma_f32_16x16x32_bf16 v[92:95], v[132:135], v[224:227], v[92:95]
	v_mfma_f32_16x16x32_bf16 v[88:91], v[140:143], v[224:227], v[88:91]
	v_mfma_f32_16x16x32_bf16 v[76:79], v[132:135], v[232:235], v[76:79]
	v_mfma_f32_16x16x32_bf16 v[72:75], v[140:143], v[232:235], v[72:75]
	s_setprio 0
	s_setprio 1
	v_mfma_f32_16x16x32_bf16 v[116:119], v[144:147], v[202:205], v[116:119]
	v_mfma_f32_16x16x32_bf16 v[112:115], v[168:171], v[202:205], v[112:115]
	v_mfma_f32_16x16x32_bf16 v[100:103], v[144:147], v[210:213], v[100:103]
	v_mfma_f32_16x16x32_bf16 v[96:99], v[168:171], v[210:213], v[96:99]
	v_mfma_f32_16x16x32_bf16 v[84:87], v[144:147], v[220:223], v[84:87]
	v_mfma_f32_16x16x32_bf16 v[80:83], v[168:171], v[220:223], v[80:83]
	v_mfma_f32_16x16x32_bf16 v[68:71], v[144:147], v[228:231], v[68:71]
	v_mfma_f32_16x16x32_bf16 v[64:67], v[168:171], v[228:231], v[64:67]
	v_mfma_f32_16x16x32_bf16 v[116:119], v[148:151], v[206:209], v[116:119]
	v_mfma_f32_16x16x32_bf16 v[112:115], v[172:175], v[206:209], v[112:115]
	v_mfma_f32_16x16x32_bf16 v[100:103], v[148:151], v[216:219], v[100:103]
	v_mfma_f32_16x16x32_bf16 v[96:99], v[172:175], v[216:219], v[96:99]
	v_mfma_f32_16x16x32_bf16 v[84:87], v[148:151], v[224:227], v[84:87]
	v_mfma_f32_16x16x32_bf16 v[80:83], v[172:175], v[224:227], v[80:83]
	v_mfma_f32_16x16x32_bf16 v[68:71], v[148:151], v[232:235], v[68:71]
	v_mfma_f32_16x16x32_bf16 v[64:67], v[172:175], v[232:235], v[64:67]
	s_setprio 0
	s_barrier
	s_add_i32 s30, s54, s17
	s_mov_b32 m0, s30
	ds_read_b128 v[202:205], v199 offset:16384
	ds_read_b128 v[206:209], v199 offset:17408
	ds_read_b128 v[210:213], v199 offset:18432
	ds_read_b128 v[216:219], v199 offset:19456
	ds_read_b128 v[220:223], v199 offset:20480
	ds_read_b128 v[224:227], v199 offset:21504
	ds_read_b128 v[228:231], v199 offset:22528
	ds_read_b128 v[232:235], v199 offset:23552
	global_load_lds_dwordx4 v154, s[46:47]
	s_add_i32 m0, s30, 0x2000
	s_add_u32 s30, s46, 0xb0000
	s_addc_u32 s31, s47, 0
	s_add_i32 s34, s55, s17
	global_load_lds_dwordx4 v158, s[46:47]
	s_mov_b32 m0, s34
	s_nop 0
	global_load_lds_dwordx4 v154, s[30:31]
	s_add_i32 m0, s34, 0x2000
	s_nop 0
	global_load_lds_dwordx4 v158, s[30:31]
	s_mov_b32 m0, s18
	s_nop 0
	global_load_lds_dwordx4 v152, s[52:53]
	s_mov_b32 m0, s19
	s_nop 0
	global_load_lds_dwordx4 v156, s[52:53]
	s_waitcnt vmcnt(8)
	s_waitcnt lgkmcnt(0)
	s_barrier
	s_setprio 1
	s_waitcnt lgkmcnt(0)
	v_mfma_f32_16x16x32_bf16 v[60:63], v[128:131], v[202:205], v[60:63]
	v_mfma_f32_16x16x32_bf16 v[56:59], v[136:139], v[202:205], v[56:59]
	v_mfma_f32_16x16x32_bf16 v[44:47], v[128:131], v[210:213], v[44:47]
	v_mfma_f32_16x16x32_bf16 v[40:43], v[136:139], v[210:213], v[40:43]
	v_mfma_f32_16x16x32_bf16 v[28:31], v[128:131], v[220:223], v[28:31]
	v_mfma_f32_16x16x32_bf16 v[24:27], v[136:139], v[220:223], v[24:27]
	v_mfma_f32_16x16x32_bf16 v[12:15], v[128:131], v[228:231], v[12:15]
	v_mfma_f32_16x16x32_bf16 v[8:11], v[136:139], v[228:231], v[8:11]
	v_mfma_f32_16x16x32_bf16 v[60:63], v[132:135], v[206:209], v[60:63]
	v_mfma_f32_16x16x32_bf16 v[56:59], v[140:143], v[206:209], v[56:59]
	v_mfma_f32_16x16x32_bf16 v[44:47], v[132:135], v[216:219], v[44:47]
	v_mfma_f32_16x16x32_bf16 v[40:43], v[140:143], v[216:219], v[40:43]
	v_mfma_f32_16x16x32_bf16 v[28:31], v[132:135], v[224:227], v[28:31]
	v_mfma_f32_16x16x32_bf16 v[24:27], v[140:143], v[224:227], v[24:27]
	v_mfma_f32_16x16x32_bf16 v[12:15], v[132:135], v[232:235], v[12:15]
	v_mfma_f32_16x16x32_bf16 v[8:11], v[140:143], v[232:235], v[8:11]
	s_setprio 0
	s_setprio 1
	v_mfma_f32_16x16x32_bf16 v[52:55], v[144:147], v[202:205], v[52:55]
	v_mfma_f32_16x16x32_bf16 v[48:51], v[168:171], v[202:205], v[48:51]
	v_mfma_f32_16x16x32_bf16 v[36:39], v[144:147], v[210:213], v[36:39]
	v_mfma_f32_16x16x32_bf16 v[32:35], v[168:171], v[210:213], v[32:35]
	v_mfma_f32_16x16x32_bf16 v[20:23], v[144:147], v[220:223], v[20:23]
	v_mfma_f32_16x16x32_bf16 v[16:19], v[168:171], v[220:223], v[16:19]
	v_mfma_f32_16x16x32_bf16 v[4:7], v[144:147], v[228:231], v[4:7]
	v_mfma_f32_16x16x32_bf16 v[0:3], v[168:171], v[228:231], v[0:3]
	v_mfma_f32_16x16x32_bf16 v[52:55], v[148:151], v[206:209], v[52:55]
	v_mfma_f32_16x16x32_bf16 v[48:51], v[172:175], v[206:209], v[48:51]
	v_mfma_f32_16x16x32_bf16 v[36:39], v[148:151], v[216:219], v[36:39]
	v_mfma_f32_16x16x32_bf16 v[32:35], v[172:175], v[216:219], v[32:35]
	v_mfma_f32_16x16x32_bf16 v[20:23], v[148:151], v[224:227], v[20:23]
	v_mfma_f32_16x16x32_bf16 v[16:19], v[172:175], v[224:227], v[16:19]
	v_mfma_f32_16x16x32_bf16 v[4:7], v[148:151], v[232:235], v[4:7]
	v_mfma_f32_16x16x32_bf16 v[0:3], v[172:175], v[232:235], v[0:3]
	s_setprio 0
	s_barrier
	s_add_i32 s34, 0, 0x18000
	s_add_i32 s35, 0, 0x1c000
	v_add_u32_e32 v140, s34, v180
	v_add_u32_e32 v172, s35, v180
	ds_read_b128 v[128:131], v140
	ds_read_b128 v[132:135], v140 offset:1024
	ds_read_b128 v[136:139], v140 offset:2048
	ds_read_b128 v[140:143], v140 offset:3072
	ds_read_b128 v[144:147], v172
	ds_read_b128 v[148:151], v172 offset:1024
	ds_read_b128 v[168:171], v172 offset:2048
	ds_read_b128 v[172:175], v172 offset:3072
	s_add_u32 s30, s52, 0xb0000
	s_addc_u32 s31, s53, 0
	s_mov_b32 m0, s20
	ds_read_b128 v[202:205], v199 offset:32768
	ds_read_b128 v[206:209], v199 offset:33792
	ds_read_b128 v[210:213], v199 offset:34816
	ds_read_b128 v[216:219], v199 offset:35840
	ds_read_b128 v[220:223], v199 offset:36864
	ds_read_b128 v[224:227], v199 offset:37888
	ds_read_b128 v[228:231], v199 offset:38912
	ds_read_b128 v[232:235], v199 offset:39936
	global_load_lds_dwordx4 v152, s[30:31]
	s_mov_b32 m0, s21
	s_nop 0
	global_load_lds_dwordx4 v156, s[30:31]
	s_waitcnt vmcnt(8)
	s_waitcnt lgkmcnt(0)
	s_barrier
	s_setprio 1
	s_waitcnt lgkmcnt(0)
	v_mfma_f32_16x16x32_bf16 v[124:127], v[128:131], v[202:205], v[124:127]
	v_mfma_f32_16x16x32_bf16 v[120:123], v[136:139], v[202:205], v[120:123]
	v_mfma_f32_16x16x32_bf16 v[108:111], v[128:131], v[210:213], v[108:111]
	v_mfma_f32_16x16x32_bf16 v[104:107], v[136:139], v[210:213], v[104:107]
	v_mfma_f32_16x16x32_bf16 v[92:95], v[128:131], v[220:223], v[92:95]
	v_mfma_f32_16x16x32_bf16 v[88:91], v[136:139], v[220:223], v[88:91]
	v_mfma_f32_16x16x32_bf16 v[76:79], v[128:131], v[228:231], v[76:79]
	v_mfma_f32_16x16x32_bf16 v[72:75], v[136:139], v[228:231], v[72:75]
	v_mfma_f32_16x16x32_bf16 v[124:127], v[132:135], v[206:209], v[124:127]
	v_mfma_f32_16x16x32_bf16 v[120:123], v[140:143], v[206:209], v[120:123]
	v_mfma_f32_16x16x32_bf16 v[108:111], v[132:135], v[216:219], v[108:111]
	v_mfma_f32_16x16x32_bf16 v[104:107], v[140:143], v[216:219], v[104:107]
	v_mfma_f32_16x16x32_bf16 v[92:95], v[132:135], v[224:227], v[92:95]
	v_mfma_f32_16x16x32_bf16 v[88:91], v[140:143], v[224:227], v[88:91]
	v_mfma_f32_16x16x32_bf16 v[76:79], v[132:135], v[232:235], v[76:79]
	v_mfma_f32_16x16x32_bf16 v[72:75], v[140:143], v[232:235], v[72:75]
	s_setprio 0
	s_setprio 1
	v_mfma_f32_16x16x32_bf16 v[116:119], v[144:147], v[202:205], v[116:119]
	v_mfma_f32_16x16x32_bf16 v[112:115], v[168:171], v[202:205], v[112:115]
	v_mfma_f32_16x16x32_bf16 v[100:103], v[144:147], v[210:213], v[100:103]
	v_mfma_f32_16x16x32_bf16 v[96:99], v[168:171], v[210:213], v[96:99]
	v_mfma_f32_16x16x32_bf16 v[84:87], v[144:147], v[220:223], v[84:87]
	v_mfma_f32_16x16x32_bf16 v[80:83], v[168:171], v[220:223], v[80:83]
	v_mfma_f32_16x16x32_bf16 v[68:71], v[144:147], v[228:231], v[68:71]
	v_mfma_f32_16x16x32_bf16 v[64:67], v[168:171], v[228:231], v[64:67]
	v_mfma_f32_16x16x32_bf16 v[116:119], v[148:151], v[206:209], v[116:119]
	v_mfma_f32_16x16x32_bf16 v[112:115], v[172:175], v[206:209], v[112:115]
	v_mfma_f32_16x16x32_bf16 v[100:103], v[148:151], v[216:219], v[100:103]
	v_mfma_f32_16x16x32_bf16 v[96:99], v[172:175], v[216:219], v[96:99]
	v_mfma_f32_16x16x32_bf16 v[84:87], v[148:151], v[224:227], v[84:87]
	v_mfma_f32_16x16x32_bf16 v[80:83], v[172:175], v[224:227], v[80:83]
	v_mfma_f32_16x16x32_bf16 v[68:71], v[148:151], v[232:235], v[68:71]
	v_mfma_f32_16x16x32_bf16 v[64:67], v[172:175], v[232:235], v[64:67]
	s_setprio 0
	s_barrier
	s_add_i32 m0, s34, s17
	s_add_u32 s30, s46, 0x80
	s_addc_u32 s31, s47, 0
	ds_read_b128 v[202:205], v199 offset:49152
	ds_read_b128 v[206:209], v199 offset:50176
	ds_read_b128 v[210:213], v199 offset:51200
	ds_read_b128 v[216:219], v199 offset:52224
	ds_read_b128 v[220:223], v199 offset:53248
	ds_read_b128 v[224:227], v199 offset:54272
	ds_read_b128 v[228:231], v199 offset:55296
	ds_read_b128 v[232:235], v199 offset:56320
	global_load_lds_dwordx4 v154, s[30:31]
	s_add_i32 m0, m0, 0x2000
	s_add_i32 s34, s35, s17
	global_load_lds_dwordx4 v158, s[30:31]
	s_add_u32 s30, s30, 0xb0000
	s_addc_u32 s31, s31, 0
	s_mov_b32 m0, s34
	s_nop 0
	global_load_lds_dwordx4 v154, s[30:31]
	s_add_i32 m0, s34, 0x2000
	s_nop 0
	global_load_lds_dwordx4 v158, s[30:31]
	s_add_u32 s30, s52, 0x80
	s_addc_u32 s31, s53, 0
	s_mov_b32 m0, s25
	s_nop 0
	global_load_lds_dwordx4 v152, s[30:31]
	s_mov_b32 m0, s26
	s_nop 0
	global_load_lds_dwordx4 v156, s[30:31]
	s_add_u32 s30, s46, 0xb0080
	s_addc_u32 s31, s47, 0
	s_waitcnt vmcnt(8)
	s_waitcnt lgkmcnt(0)
	s_barrier
	s_setprio 1
	s_waitcnt lgkmcnt(0)
	v_mfma_f32_16x16x32_bf16 v[60:63], v[128:131], v[202:205], v[60:63]
	v_mfma_f32_16x16x32_bf16 v[56:59], v[136:139], v[202:205], v[56:59]
	v_mfma_f32_16x16x32_bf16 v[44:47], v[128:131], v[210:213], v[44:47]
	v_mfma_f32_16x16x32_bf16 v[40:43], v[136:139], v[210:213], v[40:43]
	v_mfma_f32_16x16x32_bf16 v[28:31], v[128:131], v[220:223], v[28:31]
	v_mfma_f32_16x16x32_bf16 v[24:27], v[136:139], v[220:223], v[24:27]
	v_mfma_f32_16x16x32_bf16 v[12:15], v[128:131], v[228:231], v[12:15]
	v_mfma_f32_16x16x32_bf16 v[8:11], v[136:139], v[228:231], v[8:11]
	v_mfma_f32_16x16x32_bf16 v[60:63], v[132:135], v[206:209], v[60:63]
	v_mfma_f32_16x16x32_bf16 v[56:59], v[140:143], v[206:209], v[56:59]
	v_mfma_f32_16x16x32_bf16 v[44:47], v[132:135], v[216:219], v[44:47]
	v_mfma_f32_16x16x32_bf16 v[40:43], v[140:143], v[216:219], v[40:43]
	v_mfma_f32_16x16x32_bf16 v[28:31], v[132:135], v[224:227], v[28:31]
	v_mfma_f32_16x16x32_bf16 v[24:27], v[140:143], v[224:227], v[24:27]
	v_mfma_f32_16x16x32_bf16 v[12:15], v[132:135], v[232:235], v[12:15]
	v_mfma_f32_16x16x32_bf16 v[8:11], v[140:143], v[232:235], v[8:11]
	s_setprio 0
	s_setprio 1
	v_mfma_f32_16x16x32_bf16 v[52:55], v[144:147], v[202:205], v[52:55]
	v_mfma_f32_16x16x32_bf16 v[48:51], v[168:171], v[202:205], v[48:51]
	v_mfma_f32_16x16x32_bf16 v[36:39], v[144:147], v[210:213], v[36:39]
	v_mfma_f32_16x16x32_bf16 v[32:35], v[168:171], v[210:213], v[32:35]
	v_mfma_f32_16x16x32_bf16 v[20:23], v[144:147], v[220:223], v[20:23]
	v_mfma_f32_16x16x32_bf16 v[16:19], v[168:171], v[220:223], v[16:19]
	v_mfma_f32_16x16x32_bf16 v[4:7], v[144:147], v[228:231], v[4:7]
	v_mfma_f32_16x16x32_bf16 v[0:3], v[168:171], v[228:231], v[0:3]
	v_mfma_f32_16x16x32_bf16 v[52:55], v[148:151], v[206:209], v[52:55]
	v_mfma_f32_16x16x32_bf16 v[48:51], v[172:175], v[206:209], v[48:51]
	v_mfma_f32_16x16x32_bf16 v[36:39], v[148:151], v[216:219], v[36:39]
	v_mfma_f32_16x16x32_bf16 v[32:35], v[172:175], v[216:219], v[32:35]
	v_mfma_f32_16x16x32_bf16 v[20:23], v[148:151], v[224:227], v[20:23]
	v_mfma_f32_16x16x32_bf16 v[16:19], v[172:175], v[224:227], v[16:19]
	v_mfma_f32_16x16x32_bf16 v[4:7], v[148:151], v[232:235], v[4:7]
	v_mfma_f32_16x16x32_bf16 v[0:3], v[172:175], v[232:235], v[0:3]
	s_setprio 0
	s_barrier
	s_add_i32 s15, s15, 2
	s_add_u32 s13, s13, 0x100
	s_addc_u32 s14, s14, 0
	s_cmp_gt_u32 s15, 41
	s_mov_b64 s[44:45], s[42:43]
	s_cbranch_scc0 .LBB0_955
	s_and_b64 vcc, exec, s[6:7]
	s_cbranch_vccz .LBB0_958
	s_barrier
